# attention: dropped compiler vmcnt ladder guarding already-complete Q loads (kept lgkmcnt); plus de-serialised residual epilogue
# baseline (speedup 1.0000x reference)
.LBB0_331:
	s_add_i32 s13, 0, 0x12000
	v_mov_b32_e32 v0, s13
	s_waitcnt lgkmcnt(0)
	s_barrier
	ds_read_b32 v152, v0
	ds_read_b128 v[172:175], v237
	ds_read_b128 v[176:179], v237 offset:64
	ds_read_b128 v[180:183], v237 offset:2304
	ds_read_b128 v[184:187], v237 offset:2368
	ds_read_b64_tr_b16 v[156:157], v238 offset:9216
	ds_read_b64_tr_b16 v[158:159], v239 offset:9216
	ds_read_b64_tr_b16 v[160:161], v238 offset:9248
	ds_read_b64_tr_b16 v[164:165], v238 offset:9280
	ds_read_b64_tr_b16 v[168:169], v238 offset:9312
	ds_read_b64_tr_b16 v[162:163], v239 offset:9248
	ds_read_b64_tr_b16 v[166:167], v239 offset:9280
	ds_read_b64_tr_b16 v[170:171], v239 offset:9312
	s_lshl_b32 s20, s18, 1
	s_sub_i32 s21, s20, s85
	s_cmp_lt_u32 s21, 9
	s_waitcnt lgkmcnt(12)
	v_mov_b32_e32 v153, v152
	v_mov_b32_e32 v154, v152
	s_cselect_b64 s[66:67], -1, 0
	s_cmp_gt_u32 s21, 8
	v_mov_b32_e32 v155, v152
	s_cbranch_scc1 .LBB0_337
	s_cmp_lt_u32 s21, 6
	s_mov_b64 s[4:5], -1
	s_cbranch_scc1 .LBB0_334
	v_lshl_add_u32 v0, s21, 6, v233
	v_max_i32_e32 v188, 0xffffffef, v0
	v_max_i32_e32 v2, 0, v0
	v_lshl_add_u32 v193, v188, 2, s13
	v_max_i32_e32 v188, 0xffffffee, v0
	v_lshl_add_u32 v2, v2, 2, s13
	v_max_i32_e32 v3, -1, v0
	v_max_i32_e32 v5, -2, v0
	v_max_i32_e32 v6, -3, v0
	v_max_i32_e32 v7, -16, v0
	v_lshl_add_u32 v194, v188, 2, s13
	v_max_i32_e32 v0, 0xffffffed, v0
	v_lshl_add_u32 v3, v3, 2, s13
	v_lshl_add_u32 v5, v5, 2, s13
	v_lshl_add_u32 v6, v6, 2, s13
	v_lshl_add_u32 v7, v7, 2, s13
	v_lshl_add_u32 v0, v0, 2, s13
	ds_read_b32 v188, v2
	ds_read_b32 v189, v3 offset:4
	ds_read_b32 v190, v5 offset:8
	ds_read_b32 v191, v6 offset:12
	ds_read_b32 v192, v7 offset:64
	ds_read_b32 v193, v193 offset:68
	ds_read_b32 v194, v194 offset:72
	ds_read_b32 v195, v0 offset:76
	s_waitcnt lgkmcnt(4)
	v_mfma_f32_16x16x32_bf16 v[188:191], v[172:175], v[64:67], v[188:191]
	s_mov_b64 s[4:5], 0
	s_waitcnt lgkmcnt(0)
	v_mfma_f32_16x16x32_bf16 v[192:195], v[180:183], v[64:67], v[192:195]
	s_nop 0
	v_mfma_f32_16x16x32_bf16 v[188:191], v[176:179], v[68:71], v[188:191]
	v_mfma_f32_16x16x32_bf16 v[192:195], v[184:187], v[68:71], v[192:195]
.LBB0_334:
	s_andn2_b64 vcc, exec, s[4:5]
	s_cbranch_vccnz .LBB0_336
	s_waitcnt lgkmcnt(11)
	v_mfma_f32_16x16x32_bf16 v[188:191], v[172:175], v[64:67], v[152:155]
	s_waitcnt lgkmcnt(9)
	v_mfma_f32_16x16x32_bf16 v[192:195], v[180:183], v[64:67], v[152:155]
	s_nop 0
	v_mfma_f32_16x16x32_bf16 v[188:191], v[176:179], v[68:71], v[188:191]
	s_waitcnt lgkmcnt(8)
	v_mfma_f32_16x16x32_bf16 v[192:195], v[184:187], v[68:71], v[192:195]

.LBB0_337:
	s_add_i32 s14, s21, -2
	s_cmp_lt_u32 s14, 9
	s_cselect_b64 s[68:69], -1, 0
	s_cmp_gt_u32 s14, 8
	s_cbranch_scc1 .LBB0_343
	s_cmp_lt_u32 s14, 6
	s_mov_b64 s[4:5], -1
	s_cbranch_scc1 .LBB0_340
	v_lshl_add_u32 v0, s14, 6, v233
	v_max_i32_e32 v188, 0xffffffef, v0
	v_max_i32_e32 v2, 0, v0
	v_lshl_add_u32 v193, v188, 2, s13
	v_max_i32_e32 v188, 0xffffffee, v0
	v_lshl_add_u32 v2, v2, 2, s13
	v_max_i32_e32 v3, -1, v0
	v_max_i32_e32 v5, -2, v0
	v_max_i32_e32 v6, -3, v0
	v_max_i32_e32 v7, -16, v0
	v_lshl_add_u32 v194, v188, 2, s13
	v_max_i32_e32 v0, 0xffffffed, v0
	v_lshl_add_u32 v3, v3, 2, s13
	v_lshl_add_u32 v5, v5, 2, s13
	v_lshl_add_u32 v6, v6, 2, s13
	v_lshl_add_u32 v7, v7, 2, s13
	v_lshl_add_u32 v0, v0, 2, s13
	ds_read_b32 v188, v2
	ds_read_b32 v189, v3 offset:4
	ds_read_b32 v190, v5 offset:8
	ds_read_b32 v191, v6 offset:12
	ds_read_b32 v192, v7 offset:64
	ds_read_b32 v193, v193 offset:68
	ds_read_b32 v194, v194 offset:72
	ds_read_b32 v195, v0 offset:76
	s_waitcnt lgkmcnt(4)
	v_mfma_f32_16x16x32_bf16 v[188:191], v[172:175], v[76:79], v[188:191]
	s_mov_b64 s[4:5], 0
	s_waitcnt lgkmcnt(0)
	v_mfma_f32_16x16x32_bf16 v[192:195], v[180:183], v[76:79], v[192:195]
	s_nop 0
	v_mfma_f32_16x16x32_bf16 v[188:191], v[176:179], v[80:83], v[188:191]
	v_mfma_f32_16x16x32_bf16 v[192:195], v[184:187], v[80:83], v[192:195]
.LBB0_340:
	s_andn2_b64 vcc, exec, s[4:5]
	s_cbranch_vccnz .LBB0_342
	s_waitcnt lgkmcnt(11)
	v_mfma_f32_16x16x32_bf16 v[188:191], v[172:175], v[76:79], v[152:155]
	s_waitcnt lgkmcnt(9)
	v_mfma_f32_16x16x32_bf16 v[192:195], v[180:183], v[76:79], v[152:155]
	s_nop 0
	v_mfma_f32_16x16x32_bf16 v[188:191], v[176:179], v[80:83], v[188:191]
	s_waitcnt lgkmcnt(8)
	v_mfma_f32_16x16x32_bf16 v[192:195], v[184:187], v[80:83], v[192:195]

.LBB0_343:
	s_add_i32 s15, s21, -4
	s_cmp_lt_u32 s15, 9
	s_cselect_b64 s[70:71], -1, 0
	s_cmp_gt_u32 s15, 8
	s_cbranch_scc1 .LBB0_349
	s_cmp_lt_u32 s15, 6
	s_mov_b64 s[4:5], -1
	s_cbranch_scc1 .LBB0_346
	v_lshl_add_u32 v0, s15, 6, v233
	v_max_i32_e32 v188, 0xffffffef, v0
	v_max_i32_e32 v2, 0, v0
	v_lshl_add_u32 v193, v188, 2, s13
	v_max_i32_e32 v188, 0xffffffee, v0
	v_lshl_add_u32 v2, v2, 2, s13
	v_max_i32_e32 v3, -1, v0
	v_max_i32_e32 v5, -2, v0
	v_max_i32_e32 v6, -3, v0
	v_max_i32_e32 v7, -16, v0
	v_lshl_add_u32 v194, v188, 2, s13
	v_max_i32_e32 v0, 0xffffffed, v0
	v_lshl_add_u32 v3, v3, 2, s13
	v_lshl_add_u32 v5, v5, 2, s13
	v_lshl_add_u32 v6, v6, 2, s13
	v_lshl_add_u32 v7, v7, 2, s13
	v_lshl_add_u32 v0, v0, 2, s13
	ds_read_b32 v188, v2
	ds_read_b32 v189, v3 offset:4
	ds_read_b32 v190, v5 offset:8
	ds_read_b32 v191, v6 offset:12
	ds_read_b32 v192, v7 offset:64
	ds_read_b32 v193, v193 offset:68
	ds_read_b32 v194, v194 offset:72
	ds_read_b32 v195, v0 offset:76
	s_waitcnt lgkmcnt(4)
	v_mfma_f32_16x16x32_bf16 v[188:191], v[172:175], v[84:87], v[188:191]
	s_mov_b64 s[4:5], 0
	s_waitcnt lgkmcnt(0)
	v_mfma_f32_16x16x32_bf16 v[192:195], v[180:183], v[84:87], v[192:195]
	s_nop 0
	v_mfma_f32_16x16x32_bf16 v[188:191], v[176:179], v[88:91], v[188:191]
	v_mfma_f32_16x16x32_bf16 v[192:195], v[184:187], v[88:91], v[192:195]
.LBB0_346:
	s_andn2_b64 vcc, exec, s[4:5]
	s_cbranch_vccnz .LBB0_348
	s_waitcnt lgkmcnt(11)
	v_mfma_f32_16x16x32_bf16 v[188:191], v[172:175], v[84:87], v[152:155]
	s_waitcnt lgkmcnt(9)
	v_mfma_f32_16x16x32_bf16 v[192:195], v[180:183], v[84:87], v[152:155]
	s_nop 0
	v_mfma_f32_16x16x32_bf16 v[188:191], v[176:179], v[88:91], v[188:191]
	s_waitcnt lgkmcnt(8)
	v_mfma_f32_16x16x32_bf16 v[192:195], v[184:187], v[88:91], v[192:195]

.LBB0_349:
	s_add_i32 s17, s21, -6
	s_cmp_lt_u32 s17, 9
	s_cselect_b64 s[72:73], -1, 0
	s_cmp_gt_u32 s17, 8
	s_cbranch_scc1 .LBB0_355
	s_cmp_lt_u32 s17, 6
	s_mov_b64 s[4:5], -1
	s_cbranch_scc1 .LBB0_352
	v_lshl_add_u32 v0, s17, 6, v233
	v_max_i32_e32 v188, 0xffffffef, v0
	v_max_i32_e32 v2, 0, v0
	v_lshl_add_u32 v193, v188, 2, s13
	v_max_i32_e32 v188, 0xffffffee, v0
	v_lshl_add_u32 v2, v2, 2, s13
	v_max_i32_e32 v3, -1, v0
	v_max_i32_e32 v5, -2, v0
	v_max_i32_e32 v6, -3, v0
	v_max_i32_e32 v7, -16, v0
	v_lshl_add_u32 v194, v188, 2, s13
	v_max_i32_e32 v0, 0xffffffed, v0
	v_lshl_add_u32 v3, v3, 2, s13
	v_lshl_add_u32 v5, v5, 2, s13
	v_lshl_add_u32 v6, v6, 2, s13
	v_lshl_add_u32 v7, v7, 2, s13
	v_lshl_add_u32 v0, v0, 2, s13
	ds_read_b32 v188, v2
	ds_read_b32 v189, v3 offset:4
	ds_read_b32 v190, v5 offset:8
	ds_read_b32 v191, v6 offset:12
	ds_read_b32 v192, v7 offset:64
	ds_read_b32 v193, v193 offset:68
	ds_read_b32 v194, v194 offset:72
	ds_read_b32 v195, v0 offset:76
	s_waitcnt lgkmcnt(4)
	v_mfma_f32_16x16x32_bf16 v[188:191], v[172:175], v[92:95], v[188:191]
	s_mov_b64 s[4:5], 0
	s_waitcnt lgkmcnt(0)
	v_mfma_f32_16x16x32_bf16 v[192:195], v[180:183], v[92:95], v[192:195]
	s_nop 0
	v_mfma_f32_16x16x32_bf16 v[188:191], v[176:179], v[96:99], v[188:191]
	v_mfma_f32_16x16x32_bf16 v[192:195], v[184:187], v[96:99], v[192:195]
.LBB0_352:
	s_andn2_b64 vcc, exec, s[4:5]
	s_cbranch_vccnz .LBB0_354
	s_waitcnt lgkmcnt(11)
	v_mfma_f32_16x16x32_bf16 v[172:175], v[172:175], v[92:95], v[152:155]
	s_waitcnt lgkmcnt(10)
	v_mfma_f32_16x16x32_bf16 v[188:191], v[176:179], v[96:99], v[172:175]
	s_waitcnt lgkmcnt(9)
	v_mfma_f32_16x16x32_bf16 v[172:175], v[180:183], v[92:95], v[152:155]
	s_waitcnt lgkmcnt(8)
	v_mfma_f32_16x16x32_bf16 v[192:195], v[184:187], v[96:99], v[172:175]

.LBB0_359:
	s_cmp_lt_u32 s21, 6
	s_mov_b64 s[66:67], -1
	s_cbranch_scc1 .LBB0_361
	v_lshl_add_u32 v0, s21, 6, v234
	v_max_i32_e32 v188, 0xffffffef, v0
	v_max_i32_e32 v2, 0, v0
	v_lshl_add_u32 v193, v188, 2, s13
	v_max_i32_e32 v188, 0xffffffee, v0
	v_lshl_add_u32 v2, v2, 2, s13
	v_max_i32_e32 v3, -1, v0
	v_max_i32_e32 v5, -2, v0
	v_max_i32_e32 v6, -3, v0
	v_max_i32_e32 v7, -16, v0
	v_lshl_add_u32 v194, v188, 2, s13
	v_max_i32_e32 v0, 0xffffffed, v0
	v_lshl_add_u32 v3, v3, 2, s13
	v_lshl_add_u32 v5, v5, 2, s13
	v_lshl_add_u32 v6, v6, 2, s13
	v_lshl_add_u32 v7, v7, 2, s13
	v_lshl_add_u32 v0, v0, 2, s13
	ds_read_b32 v188, v2
	ds_read_b32 v189, v3 offset:4
	ds_read_b32 v190, v5 offset:8
	ds_read_b32 v191, v6 offset:12
	ds_read_b32 v192, v7 offset:64
	ds_read_b32 v193, v193 offset:68
	ds_read_b32 v194, v194 offset:72
	ds_read_b32 v195, v0 offset:76
	s_waitcnt lgkmcnt(4)
	v_mfma_f32_16x16x32_bf16 v[188:191], v[172:175], v[64:67], v[188:191]
	s_mov_b64 s[66:67], 0
	s_waitcnt lgkmcnt(0)
	v_mfma_f32_16x16x32_bf16 v[192:195], v[180:183], v[64:67], v[192:195]
	s_nop 0
	v_mfma_f32_16x16x32_bf16 v[188:191], v[176:179], v[68:71], v[188:191]
	v_mfma_f32_16x16x32_bf16 v[192:195], v[184:187], v[68:71], v[192:195]
.LBB0_361:
	s_andn2_b64 vcc, exec, s[66:67]
	s_cbranch_vccnz .LBB0_363
	s_waitcnt lgkmcnt(11)
	v_mfma_f32_16x16x32_bf16 v[188:191], v[172:175], v[64:67], v[152:155]
	s_waitcnt lgkmcnt(9)
	v_mfma_f32_16x16x32_bf16 v[192:195], v[180:183], v[64:67], v[152:155]
	s_nop 0
	v_mfma_f32_16x16x32_bf16 v[188:191], v[176:179], v[68:71], v[188:191]
	s_waitcnt lgkmcnt(8)
	v_mfma_f32_16x16x32_bf16 v[192:195], v[184:187], v[68:71], v[192:195]

.LBB0_364:
	s_cmp_lt_u32 s14, 6
	s_mov_b64 s[66:67], -1
	s_cbranch_scc1 .LBB0_366
	v_lshl_add_u32 v0, s14, 6, v234
	v_max_i32_e32 v188, 0xffffffef, v0
	v_max_i32_e32 v2, 0, v0
	v_lshl_add_u32 v193, v188, 2, s13
	v_max_i32_e32 v188, 0xffffffee, v0
	v_lshl_add_u32 v2, v2, 2, s13
	v_max_i32_e32 v3, -1, v0
	v_max_i32_e32 v5, -2, v0
	v_max_i32_e32 v6, -3, v0
	v_max_i32_e32 v7, -16, v0
	v_lshl_add_u32 v194, v188, 2, s13
	v_max_i32_e32 v0, 0xffffffed, v0
	v_lshl_add_u32 v3, v3, 2, s13
	v_lshl_add_u32 v5, v5, 2, s13
	v_lshl_add_u32 v6, v6, 2, s13
	v_lshl_add_u32 v7, v7, 2, s13
	v_lshl_add_u32 v0, v0, 2, s13
	ds_read_b32 v188, v2
	ds_read_b32 v189, v3 offset:4
	ds_read_b32 v190, v5 offset:8
	ds_read_b32 v191, v6 offset:12
	ds_read_b32 v192, v7 offset:64
	ds_read_b32 v193, v193 offset:68
	ds_read_b32 v194, v194 offset:72
	ds_read_b32 v195, v0 offset:76
	s_waitcnt lgkmcnt(4)
	v_mfma_f32_16x16x32_bf16 v[188:191], v[172:175], v[76:79], v[188:191]
	s_mov_b64 s[66:67], 0
	s_waitcnt lgkmcnt(0)
	v_mfma_f32_16x16x32_bf16 v[192:195], v[180:183], v[76:79], v[192:195]
	s_nop 0
	v_mfma_f32_16x16x32_bf16 v[188:191], v[176:179], v[80:83], v[188:191]
	v_mfma_f32_16x16x32_bf16 v[192:195], v[184:187], v[80:83], v[192:195]
.LBB0_366:
	s_andn2_b64 vcc, exec, s[66:67]
	s_cbranch_vccnz .LBB0_368
	s_waitcnt lgkmcnt(11)
	v_mfma_f32_16x16x32_bf16 v[188:191], v[172:175], v[76:79], v[152:155]
	s_waitcnt lgkmcnt(9)
	v_mfma_f32_16x16x32_bf16 v[192:195], v[180:183], v[76:79], v[152:155]
	s_nop 0
	v_mfma_f32_16x16x32_bf16 v[188:191], v[176:179], v[80:83], v[188:191]
	s_waitcnt lgkmcnt(8)
	v_mfma_f32_16x16x32_bf16 v[192:195], v[184:187], v[80:83], v[192:195]

.LBB0_369:
	s_cmp_lt_u32 s15, 6
	s_mov_b64 s[66:67], -1
	s_cbranch_scc1 .LBB0_371
	v_lshl_add_u32 v0, s15, 6, v234
	v_max_i32_e32 v188, 0xffffffef, v0
	v_max_i32_e32 v2, 0, v0
	v_lshl_add_u32 v193, v188, 2, s13
	v_max_i32_e32 v188, 0xffffffee, v0
	v_lshl_add_u32 v2, v2, 2, s13
	v_max_i32_e32 v3, -1, v0
	v_max_i32_e32 v5, -2, v0
	v_max_i32_e32 v6, -3, v0
	v_max_i32_e32 v7, -16, v0
	v_lshl_add_u32 v194, v188, 2, s13
	v_max_i32_e32 v0, 0xffffffed, v0
	v_lshl_add_u32 v3, v3, 2, s13
	v_lshl_add_u32 v5, v5, 2, s13
	v_lshl_add_u32 v6, v6, 2, s13
	v_lshl_add_u32 v7, v7, 2, s13
	v_lshl_add_u32 v0, v0, 2, s13
	ds_read_b32 v188, v2
	ds_read_b32 v189, v3 offset:4
	ds_read_b32 v190, v5 offset:8
	ds_read_b32 v191, v6 offset:12
	ds_read_b32 v192, v7 offset:64
	ds_read_b32 v193, v193 offset:68
	ds_read_b32 v194, v194 offset:72
	ds_read_b32 v195, v0 offset:76
	s_waitcnt lgkmcnt(4)
	v_mfma_f32_16x16x32_bf16 v[188:191], v[172:175], v[84:87], v[188:191]
	s_mov_b64 s[66:67], 0
	s_waitcnt lgkmcnt(0)
	v_mfma_f32_16x16x32_bf16 v[192:195], v[180:183], v[84:87], v[192:195]
	s_nop 0
	v_mfma_f32_16x16x32_bf16 v[188:191], v[176:179], v[88:91], v[188:191]
	v_mfma_f32_16x16x32_bf16 v[192:195], v[184:187], v[88:91], v[192:195]
.LBB0_371:
	s_andn2_b64 vcc, exec, s[66:67]
	s_cbranch_vccnz .LBB0_373
	s_waitcnt lgkmcnt(11)
	v_mfma_f32_16x16x32_bf16 v[188:191], v[172:175], v[84:87], v[152:155]
	s_waitcnt lgkmcnt(9)
	v_mfma_f32_16x16x32_bf16 v[192:195], v[180:183], v[84:87], v[152:155]
	s_nop 0
	v_mfma_f32_16x16x32_bf16 v[188:191], v[176:179], v[88:91], v[188:191]
	s_waitcnt lgkmcnt(8)
	v_mfma_f32_16x16x32_bf16 v[192:195], v[184:187], v[88:91], v[192:195]

.LBB0_374:
	s_cmp_lt_u32 s17, 6
	s_mov_b64 s[66:67], -1
	s_cbranch_scc1 .LBB0_376
	v_lshl_add_u32 v0, s17, 6, v234
	v_max_i32_e32 v188, 0xffffffef, v0
	v_max_i32_e32 v2, 0, v0
	v_lshl_add_u32 v193, v188, 2, s13
	v_max_i32_e32 v188, 0xffffffee, v0
	v_lshl_add_u32 v2, v2, 2, s13
	v_max_i32_e32 v3, -1, v0
	v_max_i32_e32 v5, -2, v0
	v_max_i32_e32 v6, -3, v0
	v_max_i32_e32 v7, -16, v0
	v_lshl_add_u32 v194, v188, 2, s13
	v_max_i32_e32 v0, 0xffffffed, v0
	v_lshl_add_u32 v3, v3, 2, s13
	v_lshl_add_u32 v5, v5, 2, s13
	v_lshl_add_u32 v6, v6, 2, s13
	v_lshl_add_u32 v7, v7, 2, s13
	v_lshl_add_u32 v0, v0, 2, s13
	ds_read_b32 v188, v2
	ds_read_b32 v189, v3 offset:4
	ds_read_b32 v190, v5 offset:8
	ds_read_b32 v191, v6 offset:12
	ds_read_b32 v192, v7 offset:64
	ds_read_b32 v193, v193 offset:68
	ds_read_b32 v194, v194 offset:72
	ds_read_b32 v195, v0 offset:76
	s_waitcnt lgkmcnt(4)
	v_mfma_f32_16x16x32_bf16 v[188:191], v[172:175], v[92:95], v[188:191]
	s_mov_b64 s[66:67], 0
	s_waitcnt lgkmcnt(0)
	v_mfma_f32_16x16x32_bf16 v[192:195], v[180:183], v[92:95], v[192:195]
	s_nop 0
	v_mfma_f32_16x16x32_bf16 v[188:191], v[176:179], v[96:99], v[188:191]
	v_mfma_f32_16x16x32_bf16 v[192:195], v[184:187], v[96:99], v[192:195]
.LBB0_376:
	s_andn2_b64 vcc, exec, s[66:67]
	s_cbranch_vccnz .LBB0_378
	s_waitcnt lgkmcnt(11)
	v_mfma_f32_16x16x32_bf16 v[172:175], v[172:175], v[92:95], v[152:155]
	s_waitcnt lgkmcnt(10)
	v_mfma_f32_16x16x32_bf16 v[188:191], v[176:179], v[96:99], v[172:175]
	s_waitcnt lgkmcnt(9)
	v_mfma_f32_16x16x32_bf16 v[172:175], v[180:183], v[92:95], v[152:155]
	s_waitcnt lgkmcnt(8)
	v_mfma_f32_16x16x32_bf16 v[192:195], v[184:187], v[96:99], v[172:175]

.LBB0_379:
	s_waitcnt lgkmcnt(11)
	ds_read_b128 v[172:175], v237 offset:18432
	s_waitcnt lgkmcnt(11)
	ds_read_b128 v[176:179], v237 offset:18496
	s_waitcnt lgkmcnt(11)
	ds_read_b128 v[180:183], v237 offset:20736
	s_waitcnt lgkmcnt(11)
	ds_read_b128 v[184:187], v237 offset:20800
	s_waitcnt lgkmcnt(11)
	ds_read_b64_tr_b16 v[160:161], v238 offset:27648
	s_waitcnt lgkmcnt(11)
	ds_read_b64_tr_b16 v[156:157], v238 offset:27680
	s_waitcnt lgkmcnt(11)
	ds_read_b64_tr_b16 v[164:165], v238 offset:27712
	s_waitcnt lgkmcnt(11)
	ds_read_b64_tr_b16 v[168:169], v238 offset:27744
	s_waitcnt lgkmcnt(11)
	ds_read_b64_tr_b16 v[162:163], v239 offset:27648
	s_waitcnt lgkmcnt(11)
	ds_read_b64_tr_b16 v[158:159], v239 offset:27680
	s_waitcnt lgkmcnt(11)
	ds_read_b64_tr_b16 v[166:167], v239 offset:27712
	s_waitcnt lgkmcnt(11)
	ds_read_b64_tr_b16 v[170:171], v239 offset:27744
	s_or_b32 s24, s20, 1
	s_sub_i32 s14, s24, s85
	s_cmp_lt_u32 s14, 9
	s_cselect_b64 s[66:67], -1, 0
	s_cmp_gt_u32 s14, 8
	s_cbranch_scc1 .LBB0_385
	s_cmp_lt_u32 s14, 6
	s_mov_b64 s[68:69], -1
	s_cbranch_scc1 .LBB0_382
	v_lshl_add_u32 v0, s14, 6, v233
	v_max_i32_e32 v188, 0xffffffef, v0
	v_max_i32_e32 v2, 0, v0
	v_lshl_add_u32 v193, v188, 2, s13
	v_max_i32_e32 v188, 0xffffffee, v0
	v_lshl_add_u32 v2, v2, 2, s13
	v_max_i32_e32 v3, -1, v0
	v_max_i32_e32 v5, -2, v0
	v_max_i32_e32 v6, -3, v0
	v_max_i32_e32 v7, -16, v0
	v_lshl_add_u32 v194, v188, 2, s13
	v_max_i32_e32 v0, 0xffffffed, v0
	v_lshl_add_u32 v3, v3, 2, s13
	v_lshl_add_u32 v5, v5, 2, s13
	v_lshl_add_u32 v6, v6, 2, s13
	v_lshl_add_u32 v7, v7, 2, s13
	v_lshl_add_u32 v0, v0, 2, s13
	ds_read_b32 v188, v2
	ds_read_b32 v189, v3 offset:4
	ds_read_b32 v190, v5 offset:8
	ds_read_b32 v191, v6 offset:12
	ds_read_b32 v192, v7 offset:64
	ds_read_b32 v193, v193 offset:68
	ds_read_b32 v194, v194 offset:72
	ds_read_b32 v195, v0 offset:76
	s_waitcnt lgkmcnt(4)
	v_mfma_f32_16x16x32_bf16 v[188:191], v[172:175], v[64:67], v[188:191]
	s_mov_b64 s[68:69], 0
	s_waitcnt lgkmcnt(0)
	v_mfma_f32_16x16x32_bf16 v[192:195], v[180:183], v[64:67], v[192:195]
	s_nop 0
	v_mfma_f32_16x16x32_bf16 v[188:191], v[176:179], v[68:71], v[188:191]
	v_mfma_f32_16x16x32_bf16 v[192:195], v[184:187], v[68:71], v[192:195]
.LBB0_382:
	s_andn2_b64 vcc, exec, s[68:69]
	s_cbranch_vccnz .LBB0_384
	s_waitcnt lgkmcnt(11)
	v_mfma_f32_16x16x32_bf16 v[188:191], v[172:175], v[64:67], v[152:155]
	s_waitcnt lgkmcnt(9)
	v_mfma_f32_16x16x32_bf16 v[192:195], v[180:183], v[64:67], v[152:155]
	s_nop 0
	v_mfma_f32_16x16x32_bf16 v[188:191], v[176:179], v[68:71], v[188:191]
	s_waitcnt lgkmcnt(8)
	v_mfma_f32_16x16x32_bf16 v[192:195], v[184:187], v[68:71], v[192:195]

.LBB0_385:
	s_sub_i32 s15, s24, s19
	s_cmp_lt_u32 s15, 9
	s_cselect_b64 s[68:69], -1, 0
	s_cmp_gt_u32 s15, 8
	s_cbranch_scc1 .LBB0_391
	s_cmp_lt_u32 s15, 6
	s_mov_b64 s[70:71], -1
	s_cbranch_scc1 .LBB0_388
	v_lshl_add_u32 v0, s15, 6, v233
	v_max_i32_e32 v188, 0xffffffef, v0
	v_max_i32_e32 v2, 0, v0
	v_lshl_add_u32 v193, v188, 2, s13
	v_max_i32_e32 v188, 0xffffffee, v0
	v_lshl_add_u32 v2, v2, 2, s13
	v_max_i32_e32 v3, -1, v0
	v_max_i32_e32 v5, -2, v0
	v_max_i32_e32 v6, -3, v0
	v_max_i32_e32 v7, -16, v0
	v_lshl_add_u32 v194, v188, 2, s13
	v_max_i32_e32 v0, 0xffffffed, v0
	v_lshl_add_u32 v3, v3, 2, s13
	v_lshl_add_u32 v5, v5, 2, s13
	v_lshl_add_u32 v6, v6, 2, s13
	v_lshl_add_u32 v7, v7, 2, s13
	v_lshl_add_u32 v0, v0, 2, s13
	ds_read_b32 v188, v2
	ds_read_b32 v189, v3 offset:4
	ds_read_b32 v190, v5 offset:8
	ds_read_b32 v191, v6 offset:12
	ds_read_b32 v192, v7 offset:64
	ds_read_b32 v193, v193 offset:68
	ds_read_b32 v194, v194 offset:72
	ds_read_b32 v195, v0 offset:76
	s_waitcnt lgkmcnt(4)
	v_mfma_f32_16x16x32_bf16 v[188:191], v[172:175], v[76:79], v[188:191]
	s_mov_b64 s[70:71], 0
	s_waitcnt lgkmcnt(0)
	v_mfma_f32_16x16x32_bf16 v[192:195], v[180:183], v[76:79], v[192:195]
	s_nop 0
	v_mfma_f32_16x16x32_bf16 v[188:191], v[176:179], v[80:83], v[188:191]
	v_mfma_f32_16x16x32_bf16 v[192:195], v[184:187], v[80:83], v[192:195]
.LBB0_388:
	s_andn2_b64 vcc, exec, s[70:71]
	s_cbranch_vccnz .LBB0_390
	s_waitcnt lgkmcnt(11)
	v_mfma_f32_16x16x32_bf16 v[188:191], v[172:175], v[76:79], v[152:155]
	s_waitcnt lgkmcnt(9)
	v_mfma_f32_16x16x32_bf16 v[192:195], v[180:183], v[76:79], v[152:155]
	s_nop 0
	v_mfma_f32_16x16x32_bf16 v[188:191], v[176:179], v[80:83], v[188:191]
	s_waitcnt lgkmcnt(8)
	v_mfma_f32_16x16x32_bf16 v[192:195], v[184:187], v[80:83], v[192:195]

.LBB0_391:
	s_sub_i32 s17, s24, s30
	s_cmp_lt_u32 s17, 9
	s_cselect_b64 s[70:71], -1, 0
	s_cmp_gt_u32 s17, 8
	s_cbranch_scc1 .LBB0_397
	s_cmp_lt_u32 s17, 6
	s_mov_b64 s[72:73], -1
	s_cbranch_scc1 .LBB0_394
	v_lshl_add_u32 v0, s17, 6, v233
	v_max_i32_e32 v188, 0xffffffef, v0
	v_max_i32_e32 v2, 0, v0
	v_lshl_add_u32 v193, v188, 2, s13
	v_max_i32_e32 v188, 0xffffffee, v0
	v_lshl_add_u32 v2, v2, 2, s13
	v_max_i32_e32 v3, -1, v0
	v_max_i32_e32 v5, -2, v0
	v_max_i32_e32 v6, -3, v0
	v_max_i32_e32 v7, -16, v0
	v_lshl_add_u32 v194, v188, 2, s13
	v_max_i32_e32 v0, 0xffffffed, v0
	v_lshl_add_u32 v3, v3, 2, s13
	v_lshl_add_u32 v5, v5, 2, s13
	v_lshl_add_u32 v6, v6, 2, s13
	v_lshl_add_u32 v7, v7, 2, s13
	v_lshl_add_u32 v0, v0, 2, s13
	ds_read_b32 v188, v2
	ds_read_b32 v189, v3 offset:4
	ds_read_b32 v190, v5 offset:8
	ds_read_b32 v191, v6 offset:12
	ds_read_b32 v192, v7 offset:64
	ds_read_b32 v193, v193 offset:68
	ds_read_b32 v194, v194 offset:72
	ds_read_b32 v195, v0 offset:76
	s_waitcnt lgkmcnt(4)
	v_mfma_f32_16x16x32_bf16 v[188:191], v[172:175], v[84:87], v[188:191]
	s_mov_b64 s[72:73], 0
	s_waitcnt lgkmcnt(0)
	v_mfma_f32_16x16x32_bf16 v[192:195], v[180:183], v[84:87], v[192:195]
	s_nop 0
	v_mfma_f32_16x16x32_bf16 v[188:191], v[176:179], v[88:91], v[188:191]
	v_mfma_f32_16x16x32_bf16 v[192:195], v[184:187], v[88:91], v[192:195]
.LBB0_394:
	s_andn2_b64 vcc, exec, s[72:73]
	s_cbranch_vccnz .LBB0_396
	s_waitcnt lgkmcnt(11)
	v_mfma_f32_16x16x32_bf16 v[188:191], v[172:175], v[84:87], v[152:155]
	s_waitcnt lgkmcnt(9)
	v_mfma_f32_16x16x32_bf16 v[192:195], v[180:183], v[84:87], v[152:155]
	s_nop 0
	v_mfma_f32_16x16x32_bf16 v[188:191], v[176:179], v[88:91], v[188:191]
	s_waitcnt lgkmcnt(8)
	v_mfma_f32_16x16x32_bf16 v[192:195], v[184:187], v[88:91], v[192:195]

.LBB0_397:
	s_sub_i32 s24, s24, s34
	s_cmp_lt_u32 s24, 9
	s_cselect_b64 s[72:73], -1, 0
	s_cmp_gt_u32 s24, 8
	s_cbranch_scc1 .LBB0_403
	s_cmp_lt_u32 s24, 6
	s_mov_b64 s[74:75], -1
	s_cbranch_scc1 .LBB0_400
	v_lshl_add_u32 v0, s24, 6, v233
	v_max_i32_e32 v188, 0xffffffef, v0
	v_max_i32_e32 v2, 0, v0
	v_lshl_add_u32 v193, v188, 2, s13
	v_max_i32_e32 v188, 0xffffffee, v0
	v_lshl_add_u32 v2, v2, 2, s13
	v_max_i32_e32 v3, -1, v0
	v_max_i32_e32 v5, -2, v0
	v_max_i32_e32 v6, -3, v0
	v_max_i32_e32 v7, -16, v0
	v_lshl_add_u32 v194, v188, 2, s13
	v_max_i32_e32 v0, 0xffffffed, v0
	v_lshl_add_u32 v3, v3, 2, s13
	v_lshl_add_u32 v5, v5, 2, s13
	v_lshl_add_u32 v6, v6, 2, s13
	v_lshl_add_u32 v7, v7, 2, s13
	v_lshl_add_u32 v0, v0, 2, s13
	ds_read_b32 v188, v2
	ds_read_b32 v189, v3 offset:4
	ds_read_b32 v190, v5 offset:8
	ds_read_b32 v191, v6 offset:12
	ds_read_b32 v192, v7 offset:64
	ds_read_b32 v193, v193 offset:68
	ds_read_b32 v194, v194 offset:72
	ds_read_b32 v195, v0 offset:76
	s_waitcnt lgkmcnt(4)
	v_mfma_f32_16x16x32_bf16 v[188:191], v[172:175], v[92:95], v[188:191]
	s_mov_b64 s[74:75], 0
	s_waitcnt lgkmcnt(0)
	v_mfma_f32_16x16x32_bf16 v[192:195], v[180:183], v[92:95], v[192:195]
	s_nop 0
	v_mfma_f32_16x16x32_bf16 v[188:191], v[176:179], v[96:99], v[188:191]
	v_mfma_f32_16x16x32_bf16 v[192:195], v[184:187], v[96:99], v[192:195]
.LBB0_400:
	s_andn2_b64 vcc, exec, s[74:75]
	s_cbranch_vccnz .LBB0_402
	s_waitcnt lgkmcnt(11)
	v_mfma_f32_16x16x32_bf16 v[172:175], v[172:175], v[92:95], v[152:155]
	s_waitcnt lgkmcnt(10)
	v_mfma_f32_16x16x32_bf16 v[188:191], v[176:179], v[96:99], v[172:175]
	s_waitcnt lgkmcnt(9)
	v_mfma_f32_16x16x32_bf16 v[172:175], v[180:183], v[92:95], v[152:155]
	s_waitcnt lgkmcnt(8)
	v_mfma_f32_16x16x32_bf16 v[192:195], v[184:187], v[96:99], v[172:175]

.LBB0_407:
	s_cmp_lt_u32 s14, 6
	s_mov_b64 s[66:67], -1
	s_cbranch_scc1 .LBB0_409
	v_lshl_add_u32 v0, s14, 6, v234
	v_max_i32_e32 v188, 0xffffffef, v0
	v_max_i32_e32 v2, 0, v0
	v_lshl_add_u32 v193, v188, 2, s13
	v_max_i32_e32 v188, 0xffffffee, v0
	v_lshl_add_u32 v2, v2, 2, s13
	v_max_i32_e32 v3, -1, v0
	v_max_i32_e32 v5, -2, v0
	v_max_i32_e32 v6, -3, v0
	v_max_i32_e32 v7, -16, v0
	v_lshl_add_u32 v194, v188, 2, s13
	v_max_i32_e32 v0, 0xffffffed, v0
	v_lshl_add_u32 v3, v3, 2, s13
	v_lshl_add_u32 v5, v5, 2, s13
	v_lshl_add_u32 v6, v6, 2, s13
	v_lshl_add_u32 v7, v7, 2, s13
	v_lshl_add_u32 v0, v0, 2, s13
	ds_read_b32 v188, v2
	ds_read_b32 v189, v3 offset:4
	ds_read_b32 v190, v5 offset:8
	ds_read_b32 v191, v6 offset:12
	ds_read_b32 v192, v7 offset:64
	ds_read_b32 v193, v193 offset:68
	ds_read_b32 v194, v194 offset:72
	ds_read_b32 v195, v0 offset:76
	s_waitcnt lgkmcnt(4)
	v_mfma_f32_16x16x32_bf16 v[188:191], v[172:175], v[64:67], v[188:191]
	s_mov_b64 s[66:67], 0
	s_waitcnt lgkmcnt(0)
	v_mfma_f32_16x16x32_bf16 v[192:195], v[180:183], v[64:67], v[192:195]
	s_nop 0
	v_mfma_f32_16x16x32_bf16 v[188:191], v[176:179], v[68:71], v[188:191]
	v_mfma_f32_16x16x32_bf16 v[192:195], v[184:187], v[68:71], v[192:195]

.LBB0_412:
	s_cmp_lt_u32 s15, 6
	s_mov_b64 s[66:67], -1
	s_cbranch_scc1 .LBB0_414
	v_lshl_add_u32 v0, s15, 6, v234
	v_max_i32_e32 v188, 0xffffffef, v0
	v_max_i32_e32 v2, 0, v0
	v_lshl_add_u32 v193, v188, 2, s13
	v_max_i32_e32 v188, 0xffffffee, v0
	v_lshl_add_u32 v2, v2, 2, s13
	v_max_i32_e32 v3, -1, v0
	v_max_i32_e32 v5, -2, v0
	v_max_i32_e32 v6, -3, v0
	v_max_i32_e32 v7, -16, v0
	v_lshl_add_u32 v194, v188, 2, s13
	v_max_i32_e32 v0, 0xffffffed, v0
	v_lshl_add_u32 v3, v3, 2, s13
	v_lshl_add_u32 v5, v5, 2, s13
	v_lshl_add_u32 v6, v6, 2, s13
	v_lshl_add_u32 v7, v7, 2, s13
	v_lshl_add_u32 v0, v0, 2, s13
	ds_read_b32 v188, v2
	ds_read_b32 v189, v3 offset:4
	ds_read_b32 v190, v5 offset:8
	ds_read_b32 v191, v6 offset:12
	ds_read_b32 v192, v7 offset:64
	ds_read_b32 v193, v193 offset:68
	ds_read_b32 v194, v194 offset:72
	ds_read_b32 v195, v0 offset:76
	s_waitcnt lgkmcnt(4)
	v_mfma_f32_16x16x32_bf16 v[188:191], v[172:175], v[76:79], v[188:191]
	s_mov_b64 s[66:67], 0
	s_waitcnt lgkmcnt(0)
	v_mfma_f32_16x16x32_bf16 v[192:195], v[180:183], v[76:79], v[192:195]
	s_nop 0
	v_mfma_f32_16x16x32_bf16 v[188:191], v[176:179], v[80:83], v[188:191]
	v_mfma_f32_16x16x32_bf16 v[192:195], v[184:187], v[80:83], v[192:195]

.LBB0_417:
	s_cmp_lt_u32 s17, 6
	s_mov_b64 s[66:67], -1
	s_cbranch_scc1 .LBB0_419
	v_lshl_add_u32 v0, s17, 6, v234
	v_max_i32_e32 v188, 0xffffffef, v0
	v_max_i32_e32 v2, 0, v0
	v_lshl_add_u32 v193, v188, 2, s13
	v_max_i32_e32 v188, 0xffffffee, v0
	v_lshl_add_u32 v2, v2, 2, s13
	v_max_i32_e32 v3, -1, v0
	v_max_i32_e32 v5, -2, v0
	v_max_i32_e32 v6, -3, v0
	v_max_i32_e32 v7, -16, v0
	v_lshl_add_u32 v194, v188, 2, s13
	v_max_i32_e32 v0, 0xffffffed, v0
	v_lshl_add_u32 v3, v3, 2, s13
	v_lshl_add_u32 v5, v5, 2, s13
	v_lshl_add_u32 v6, v6, 2, s13
	v_lshl_add_u32 v7, v7, 2, s13
	v_lshl_add_u32 v0, v0, 2, s13
	ds_read_b32 v188, v2
	ds_read_b32 v189, v3 offset:4
	ds_read_b32 v190, v5 offset:8
	ds_read_b32 v191, v6 offset:12
	ds_read_b32 v192, v7 offset:64
	ds_read_b32 v193, v193 offset:68
	ds_read_b32 v194, v194 offset:72
	ds_read_b32 v195, v0 offset:76
	s_waitcnt lgkmcnt(4)
	v_mfma_f32_16x16x32_bf16 v[188:191], v[172:175], v[84:87], v[188:191]
	s_mov_b64 s[66:67], 0
	s_waitcnt lgkmcnt(0)
	v_mfma_f32_16x16x32_bf16 v[192:195], v[180:183], v[84:87], v[192:195]
	s_nop 0
	v_mfma_f32_16x16x32_bf16 v[188:191], v[176:179], v[88:91], v[188:191]
	v_mfma_f32_16x16x32_bf16 v[192:195], v[184:187], v[88:91], v[192:195]

.LBB0_422:
	s_cmp_lt_u32 s24, 6
	s_mov_b64 s[66:67], -1
	s_cbranch_scc1 .LBB0_424
	v_lshl_add_u32 v0, s24, 6, v234
	v_max_i32_e32 v188, 0xffffffef, v0
	v_max_i32_e32 v2, 0, v0
	v_lshl_add_u32 v193, v188, 2, s13
	v_max_i32_e32 v188, 0xffffffee, v0
	v_lshl_add_u32 v2, v2, 2, s13
	v_max_i32_e32 v3, -1, v0
	v_max_i32_e32 v5, -2, v0
	v_max_i32_e32 v6, -3, v0
	v_max_i32_e32 v7, -16, v0
	v_lshl_add_u32 v194, v188, 2, s13
	v_max_i32_e32 v0, 0xffffffed, v0
	v_lshl_add_u32 v3, v3, 2, s13
	v_lshl_add_u32 v5, v5, 2, s13
	v_lshl_add_u32 v6, v6, 2, s13
	v_lshl_add_u32 v7, v7, 2, s13
	v_lshl_add_u32 v0, v0, 2, s13
	ds_read_b32 v188, v2
	ds_read_b32 v189, v3 offset:4
	ds_read_b32 v190, v5 offset:8
	ds_read_b32 v191, v6 offset:12
	ds_read_b32 v192, v7 offset:64
	ds_read_b32 v193, v193 offset:68
	ds_read_b32 v194, v194 offset:72
	ds_read_b32 v195, v0 offset:76
	s_waitcnt lgkmcnt(4)
	v_mfma_f32_16x16x32_bf16 v[188:191], v[172:175], v[92:95], v[188:191]
	s_mov_b64 s[66:67], 0
	s_waitcnt lgkmcnt(0)
	v_mfma_f32_16x16x32_bf16 v[192:195], v[180:183], v[92:95], v[192:195]
	s_nop 0
	v_mfma_f32_16x16x32_bf16 v[188:191], v[176:179], v[96:99], v[188:191]
	v_mfma_f32_16x16x32_bf16 v[192:195], v[184:187], v[96:99], v[192:195]
.LBB0_424:
	s_andn2_b64 vcc, exec, s[66:67]
	s_cbranch_vccnz .LBB0_426
	s_waitcnt lgkmcnt(11)
	v_mfma_f32_16x16x32_bf16 v[172:175], v[172:175], v[92:95], v[152:155]
	s_waitcnt lgkmcnt(9)
	v_mfma_f32_16x16x32_bf16 v[152:155], v[180:183], v[92:95], v[152:155]
	s_nop 0
	v_mfma_f32_16x16x32_bf16 v[188:191], v[176:179], v[96:99], v[172:175]
	s_waitcnt lgkmcnt(8)
	v_mfma_f32_16x16x32_bf16 v[192:195], v[184:187], v[96:99], v[152:155]

.LBB0_434:
	v_mov_b32_e32 v0, s13
	s_waitcnt lgkmcnt(0)
	s_barrier
	ds_read_b32 v152, v0
	ds_read_b128 v[172:175], v237 offset:36864
	ds_read_b128 v[176:179], v237 offset:36928
	ds_read_b128 v[180:183], v237 offset:39168
	ds_read_b128 v[184:187], v237 offset:39232
	ds_read_b64_tr_b16 v[160:161], v238 offset:46080
	ds_read_b64_tr_b16 v[156:157], v238 offset:46112
	ds_read_b64_tr_b16 v[164:165], v238 offset:46144
	ds_read_b64_tr_b16 v[168:169], v238 offset:46176
	ds_read_b64_tr_b16 v[162:163], v239 offset:46080
	ds_read_b64_tr_b16 v[158:159], v239 offset:46112
	ds_read_b64_tr_b16 v[166:167], v239 offset:46144
	ds_read_b64_tr_b16 v[170:171], v239 offset:46176
	s_or_b32 s17, s20, 2
	s_sub_i32 s14, s17, s85
	s_cmp_lt_u32 s14, 9
	s_waitcnt lgkmcnt(12)
	v_mov_b32_e32 v153, v152
	v_mov_b32_e32 v154, v152
	s_cselect_b64 s[70:71], -1, 0
	s_cmp_gt_u32 s14, 8
	v_mov_b32_e32 v155, v152
	s_cbranch_scc1 .LBB0_440
	s_cmp_lt_u32 s14, 6
	s_mov_b64 s[72:73], -1
	s_cbranch_scc1 .LBB0_437
	v_lshl_add_u32 v0, s14, 6, v233
	v_max_i32_e32 v188, 0xffffffef, v0
	v_max_i32_e32 v2, 0, v0
	v_lshl_add_u32 v193, v188, 2, s13
	v_max_i32_e32 v188, 0xffffffee, v0
	v_lshl_add_u32 v2, v2, 2, s13
	v_max_i32_e32 v3, -1, v0
	v_max_i32_e32 v5, -2, v0
	v_max_i32_e32 v6, -3, v0
	v_max_i32_e32 v7, -16, v0
	v_lshl_add_u32 v194, v188, 2, s13
	v_max_i32_e32 v0, 0xffffffed, v0
	v_lshl_add_u32 v3, v3, 2, s13
	v_lshl_add_u32 v5, v5, 2, s13
	v_lshl_add_u32 v6, v6, 2, s13
	v_lshl_add_u32 v7, v7, 2, s13
	v_lshl_add_u32 v0, v0, 2, s13
	ds_read_b32 v188, v2
	ds_read_b32 v189, v3 offset:4
	ds_read_b32 v190, v5 offset:8
	ds_read_b32 v191, v6 offset:12
	ds_read_b32 v192, v7 offset:64
	ds_read_b32 v193, v193 offset:68
	ds_read_b32 v194, v194 offset:72
	ds_read_b32 v195, v0 offset:76
	s_waitcnt lgkmcnt(4)
	v_mfma_f32_16x16x32_bf16 v[188:191], v[172:175], v[64:67], v[188:191]
	s_mov_b64 s[72:73], 0
	s_waitcnt lgkmcnt(0)
	v_mfma_f32_16x16x32_bf16 v[192:195], v[180:183], v[64:67], v[192:195]
	s_nop 0
	v_mfma_f32_16x16x32_bf16 v[188:191], v[176:179], v[68:71], v[188:191]
	v_mfma_f32_16x16x32_bf16 v[192:195], v[184:187], v[68:71], v[192:195]
.LBB0_437:
	s_andn2_b64 vcc, exec, s[72:73]
	s_cbranch_vccnz .LBB0_439
	s_waitcnt lgkmcnt(11)
	v_mfma_f32_16x16x32_bf16 v[188:191], v[172:175], v[64:67], v[152:155]
	s_waitcnt lgkmcnt(9)
	v_mfma_f32_16x16x32_bf16 v[192:195], v[180:183], v[64:67], v[152:155]
	s_nop 0
	v_mfma_f32_16x16x32_bf16 v[188:191], v[176:179], v[68:71], v[188:191]
	s_waitcnt lgkmcnt(8)
	v_mfma_f32_16x16x32_bf16 v[192:195], v[184:187], v[68:71], v[192:195]

.LBB0_440:
	s_and_b64 vcc, exec, s[4:5]
	s_cbranch_vccnz .LBB0_446
	s_cmp_lt_u32 s21, 6
	s_mov_b64 s[72:73], -1
	s_cbranch_scc1 .LBB0_443
	v_lshl_add_u32 v0, s21, 6, v233
	v_max_i32_e32 v188, 0xffffffef, v0
	v_max_i32_e32 v2, 0, v0
	v_lshl_add_u32 v193, v188, 2, s13
	v_max_i32_e32 v188, 0xffffffee, v0
	v_lshl_add_u32 v2, v2, 2, s13
	v_max_i32_e32 v3, -1, v0
	v_max_i32_e32 v5, -2, v0
	v_max_i32_e32 v6, -3, v0
	v_max_i32_e32 v7, -16, v0
	v_lshl_add_u32 v194, v188, 2, s13
	v_max_i32_e32 v0, 0xffffffed, v0
	v_lshl_add_u32 v3, v3, 2, s13
	v_lshl_add_u32 v5, v5, 2, s13
	v_lshl_add_u32 v6, v6, 2, s13
	v_lshl_add_u32 v7, v7, 2, s13
	v_lshl_add_u32 v0, v0, 2, s13
	ds_read_b32 v188, v2
	ds_read_b32 v189, v3 offset:4
	ds_read_b32 v190, v5 offset:8
	ds_read_b32 v191, v6 offset:12
	ds_read_b32 v192, v7 offset:64
	ds_read_b32 v193, v193 offset:68
	ds_read_b32 v194, v194 offset:72
	ds_read_b32 v195, v0 offset:76
	s_waitcnt lgkmcnt(4)
	v_mfma_f32_16x16x32_bf16 v[188:191], v[172:175], v[76:79], v[188:191]
	s_mov_b64 s[72:73], 0
	s_waitcnt lgkmcnt(0)
	v_mfma_f32_16x16x32_bf16 v[192:195], v[180:183], v[76:79], v[192:195]
	s_nop 0
	v_mfma_f32_16x16x32_bf16 v[188:191], v[176:179], v[80:83], v[188:191]
	v_mfma_f32_16x16x32_bf16 v[192:195], v[184:187], v[80:83], v[192:195]
.LBB0_443:
	s_andn2_b64 vcc, exec, s[72:73]
	s_cbranch_vccnz .LBB0_445
	s_waitcnt lgkmcnt(11)
	v_mfma_f32_16x16x32_bf16 v[188:191], v[172:175], v[76:79], v[152:155]
	s_waitcnt lgkmcnt(9)
	v_mfma_f32_16x16x32_bf16 v[192:195], v[180:183], v[76:79], v[152:155]
	s_nop 0
	v_mfma_f32_16x16x32_bf16 v[188:191], v[176:179], v[80:83], v[188:191]
	s_waitcnt lgkmcnt(8)
	v_mfma_f32_16x16x32_bf16 v[192:195], v[184:187], v[80:83], v[192:195]

.LBB0_446:
	s_sub_i32 s15, s17, s30
	s_cmp_lt_u32 s15, 9
	s_cselect_b64 s[72:73], -1, 0
	s_cmp_gt_u32 s15, 8
	s_cbranch_scc1 .LBB0_452
	s_cmp_lt_u32 s15, 6
	s_mov_b64 s[74:75], -1
	s_cbranch_scc1 .LBB0_449
	v_lshl_add_u32 v0, s15, 6, v233
	v_max_i32_e32 v188, 0xffffffef, v0
	v_max_i32_e32 v2, 0, v0
	v_lshl_add_u32 v193, v188, 2, s13
	v_max_i32_e32 v188, 0xffffffee, v0
	v_lshl_add_u32 v2, v2, 2, s13
	v_max_i32_e32 v3, -1, v0
	v_max_i32_e32 v5, -2, v0
	v_max_i32_e32 v6, -3, v0
	v_max_i32_e32 v7, -16, v0
	v_lshl_add_u32 v194, v188, 2, s13
	v_max_i32_e32 v0, 0xffffffed, v0
	v_lshl_add_u32 v3, v3, 2, s13
	v_lshl_add_u32 v5, v5, 2, s13
	v_lshl_add_u32 v6, v6, 2, s13
	v_lshl_add_u32 v7, v7, 2, s13
	v_lshl_add_u32 v0, v0, 2, s13
	ds_read_b32 v188, v2
	ds_read_b32 v189, v3 offset:4
	ds_read_b32 v190, v5 offset:8
	ds_read_b32 v191, v6 offset:12
	ds_read_b32 v192, v7 offset:64
	ds_read_b32 v193, v193 offset:68
	ds_read_b32 v194, v194 offset:72
	ds_read_b32 v195, v0 offset:76
	s_waitcnt lgkmcnt(4)
	v_mfma_f32_16x16x32_bf16 v[188:191], v[172:175], v[84:87], v[188:191]
	s_mov_b64 s[74:75], 0
	s_waitcnt lgkmcnt(0)
	v_mfma_f32_16x16x32_bf16 v[192:195], v[180:183], v[84:87], v[192:195]
	s_nop 0
	v_mfma_f32_16x16x32_bf16 v[188:191], v[176:179], v[88:91], v[188:191]
	v_mfma_f32_16x16x32_bf16 v[192:195], v[184:187], v[88:91], v[192:195]
.LBB0_449:
	s_andn2_b64 vcc, exec, s[74:75]
	s_cbranch_vccnz .LBB0_451
	s_waitcnt lgkmcnt(11)
	v_mfma_f32_16x16x32_bf16 v[188:191], v[172:175], v[84:87], v[152:155]
	s_waitcnt lgkmcnt(9)
	v_mfma_f32_16x16x32_bf16 v[192:195], v[180:183], v[84:87], v[152:155]
	s_nop 0
	v_mfma_f32_16x16x32_bf16 v[188:191], v[176:179], v[88:91], v[188:191]
	s_waitcnt lgkmcnt(8)
	v_mfma_f32_16x16x32_bf16 v[192:195], v[184:187], v[88:91], v[192:195]

.LBB0_452:
	s_sub_i32 s17, s17, s34
	s_cmp_lt_u32 s17, 9
	s_cselect_b64 s[74:75], -1, 0
	s_cmp_gt_u32 s17, 8
	s_cbranch_scc1 .LBB0_458
	s_cmp_lt_u32 s17, 6
	s_mov_b64 s[76:77], -1
	s_cbranch_scc1 .LBB0_455
	v_lshl_add_u32 v0, s17, 6, v233
	v_max_i32_e32 v188, 0xffffffef, v0
	v_max_i32_e32 v2, 0, v0
	v_lshl_add_u32 v193, v188, 2, s13
	v_max_i32_e32 v188, 0xffffffee, v0
	v_lshl_add_u32 v2, v2, 2, s13
	v_max_i32_e32 v3, -1, v0
	v_max_i32_e32 v5, -2, v0
	v_max_i32_e32 v6, -3, v0
	v_max_i32_e32 v7, -16, v0
	v_lshl_add_u32 v194, v188, 2, s13
	v_max_i32_e32 v0, 0xffffffed, v0
	v_lshl_add_u32 v3, v3, 2, s13
	v_lshl_add_u32 v5, v5, 2, s13
	v_lshl_add_u32 v6, v6, 2, s13
	v_lshl_add_u32 v7, v7, 2, s13
	v_lshl_add_u32 v0, v0, 2, s13
	ds_read_b32 v188, v2
	ds_read_b32 v189, v3 offset:4
	ds_read_b32 v190, v5 offset:8
	ds_read_b32 v191, v6 offset:12
	ds_read_b32 v192, v7 offset:64
	ds_read_b32 v193, v193 offset:68
	ds_read_b32 v194, v194 offset:72
	ds_read_b32 v195, v0 offset:76
	s_waitcnt lgkmcnt(4)
	v_mfma_f32_16x16x32_bf16 v[188:191], v[172:175], v[92:95], v[188:191]
	s_mov_b64 s[76:77], 0
	s_waitcnt lgkmcnt(0)
	v_mfma_f32_16x16x32_bf16 v[192:195], v[180:183], v[92:95], v[192:195]
	s_nop 0
	v_mfma_f32_16x16x32_bf16 v[188:191], v[176:179], v[96:99], v[188:191]
	v_mfma_f32_16x16x32_bf16 v[192:195], v[184:187], v[96:99], v[192:195]
.LBB0_455:
	s_andn2_b64 vcc, exec, s[76:77]
	s_cbranch_vccnz .LBB0_457
	s_waitcnt lgkmcnt(11)
	v_mfma_f32_16x16x32_bf16 v[172:175], v[172:175], v[92:95], v[152:155]
	s_waitcnt lgkmcnt(10)
	v_mfma_f32_16x16x32_bf16 v[188:191], v[176:179], v[96:99], v[172:175]
	s_waitcnt lgkmcnt(9)
	v_mfma_f32_16x16x32_bf16 v[172:175], v[180:183], v[92:95], v[152:155]
	s_waitcnt lgkmcnt(8)
	v_mfma_f32_16x16x32_bf16 v[192:195], v[184:187], v[96:99], v[172:175]

.LBB0_462:
	s_cmp_lt_u32 s14, 6
	s_mov_b64 s[70:71], -1
	s_cbranch_scc1 .LBB0_464
	v_lshl_add_u32 v0, s14, 6, v234
	v_max_i32_e32 v188, 0xffffffef, v0
	v_max_i32_e32 v2, 0, v0
	v_lshl_add_u32 v193, v188, 2, s13
	v_max_i32_e32 v188, 0xffffffee, v0
	v_lshl_add_u32 v2, v2, 2, s13
	v_max_i32_e32 v3, -1, v0
	v_max_i32_e32 v5, -2, v0
	v_max_i32_e32 v6, -3, v0
	v_max_i32_e32 v7, -16, v0
	v_lshl_add_u32 v194, v188, 2, s13
	v_max_i32_e32 v0, 0xffffffed, v0
	v_lshl_add_u32 v3, v3, 2, s13
	v_lshl_add_u32 v5, v5, 2, s13
	v_lshl_add_u32 v6, v6, 2, s13
	v_lshl_add_u32 v7, v7, 2, s13
	v_lshl_add_u32 v0, v0, 2, s13
	ds_read_b32 v188, v2
	ds_read_b32 v189, v3 offset:4
	ds_read_b32 v190, v5 offset:8
	ds_read_b32 v191, v6 offset:12
	ds_read_b32 v192, v7 offset:64
	ds_read_b32 v193, v193 offset:68
	ds_read_b32 v194, v194 offset:72
	ds_read_b32 v195, v0 offset:76
	s_waitcnt lgkmcnt(4)
	v_mfma_f32_16x16x32_bf16 v[188:191], v[172:175], v[64:67], v[188:191]
	s_mov_b64 s[70:71], 0
	s_waitcnt lgkmcnt(0)
	v_mfma_f32_16x16x32_bf16 v[192:195], v[180:183], v[64:67], v[192:195]
	s_nop 0
	v_mfma_f32_16x16x32_bf16 v[188:191], v[176:179], v[68:71], v[188:191]
	v_mfma_f32_16x16x32_bf16 v[192:195], v[184:187], v[68:71], v[192:195]
.LBB0_464:
	s_andn2_b64 vcc, exec, s[70:71]
	s_cbranch_vccnz .LBB0_466
	s_waitcnt lgkmcnt(11)
	v_mfma_f32_16x16x32_bf16 v[188:191], v[172:175], v[64:67], v[152:155]
	s_waitcnt lgkmcnt(9)
	v_mfma_f32_16x16x32_bf16 v[192:195], v[180:183], v[64:67], v[152:155]
	s_nop 0
	v_mfma_f32_16x16x32_bf16 v[188:191], v[176:179], v[68:71], v[188:191]
	s_waitcnt lgkmcnt(8)
	v_mfma_f32_16x16x32_bf16 v[192:195], v[184:187], v[68:71], v[192:195]

.LBB0_467:
	s_cmp_lt_u32 s21, 6
	s_mov_b64 s[4:5], -1
	s_cbranch_scc1 .LBB0_469
	v_lshl_add_u32 v0, s21, 6, v234
	v_max_i32_e32 v188, 0xffffffef, v0
	v_max_i32_e32 v2, 0, v0
	v_lshl_add_u32 v193, v188, 2, s13
	v_max_i32_e32 v188, 0xffffffee, v0
	v_lshl_add_u32 v2, v2, 2, s13
	v_max_i32_e32 v3, -1, v0
	v_max_i32_e32 v5, -2, v0
	v_max_i32_e32 v6, -3, v0
	v_max_i32_e32 v7, -16, v0
	v_lshl_add_u32 v194, v188, 2, s13
	v_max_i32_e32 v0, 0xffffffed, v0
	v_lshl_add_u32 v3, v3, 2, s13
	v_lshl_add_u32 v5, v5, 2, s13
	v_lshl_add_u32 v6, v6, 2, s13
	v_lshl_add_u32 v7, v7, 2, s13
	v_lshl_add_u32 v0, v0, 2, s13
	ds_read_b32 v188, v2
	ds_read_b32 v189, v3 offset:4
	ds_read_b32 v190, v5 offset:8
	ds_read_b32 v191, v6 offset:12
	ds_read_b32 v192, v7 offset:64
	ds_read_b32 v193, v193 offset:68
	ds_read_b32 v194, v194 offset:72
	ds_read_b32 v195, v0 offset:76
	s_waitcnt lgkmcnt(4)
	v_mfma_f32_16x16x32_bf16 v[188:191], v[172:175], v[76:79], v[188:191]
	s_mov_b64 s[4:5], 0
	s_waitcnt lgkmcnt(0)
	v_mfma_f32_16x16x32_bf16 v[192:195], v[180:183], v[76:79], v[192:195]
	s_nop 0
	v_mfma_f32_16x16x32_bf16 v[188:191], v[176:179], v[80:83], v[188:191]
	v_mfma_f32_16x16x32_bf16 v[192:195], v[184:187], v[80:83], v[192:195]

.LBB0_472:
	s_cmp_lt_u32 s15, 6
	s_mov_b64 s[4:5], -1
	s_cbranch_scc1 .LBB0_474
	v_lshl_add_u32 v0, s15, 6, v234
	v_max_i32_e32 v188, 0xffffffef, v0
	v_max_i32_e32 v2, 0, v0
	v_lshl_add_u32 v193, v188, 2, s13
	v_max_i32_e32 v188, 0xffffffee, v0
	v_lshl_add_u32 v2, v2, 2, s13
	v_max_i32_e32 v3, -1, v0
	v_max_i32_e32 v5, -2, v0
	v_max_i32_e32 v6, -3, v0
	v_max_i32_e32 v7, -16, v0
	v_lshl_add_u32 v194, v188, 2, s13
	v_max_i32_e32 v0, 0xffffffed, v0
	v_lshl_add_u32 v3, v3, 2, s13
	v_lshl_add_u32 v5, v5, 2, s13
	v_lshl_add_u32 v6, v6, 2, s13
	v_lshl_add_u32 v7, v7, 2, s13
	v_lshl_add_u32 v0, v0, 2, s13
	ds_read_b32 v188, v2
	ds_read_b32 v189, v3 offset:4
	ds_read_b32 v190, v5 offset:8
	ds_read_b32 v191, v6 offset:12
	ds_read_b32 v192, v7 offset:64
	ds_read_b32 v193, v193 offset:68
	ds_read_b32 v194, v194 offset:72
	ds_read_b32 v195, v0 offset:76
	s_waitcnt lgkmcnt(4)
	v_mfma_f32_16x16x32_bf16 v[188:191], v[172:175], v[84:87], v[188:191]
	s_mov_b64 s[4:5], 0
	s_waitcnt lgkmcnt(0)
	v_mfma_f32_16x16x32_bf16 v[192:195], v[180:183], v[84:87], v[192:195]
	s_nop 0
	v_mfma_f32_16x16x32_bf16 v[188:191], v[176:179], v[88:91], v[188:191]
	v_mfma_f32_16x16x32_bf16 v[192:195], v[184:187], v[88:91], v[192:195]

.LBB0_477:
	s_cmp_lt_u32 s17, 6
	s_mov_b64 s[4:5], -1
	s_cbranch_scc1 .LBB0_479
	v_lshl_add_u32 v0, s17, 6, v234
	v_max_i32_e32 v188, 0xffffffef, v0
	v_max_i32_e32 v2, 0, v0
	v_lshl_add_u32 v193, v188, 2, s13
	v_max_i32_e32 v188, 0xffffffee, v0
	v_lshl_add_u32 v2, v2, 2, s13
	v_max_i32_e32 v3, -1, v0
	v_max_i32_e32 v5, -2, v0
	v_max_i32_e32 v6, -3, v0
	v_max_i32_e32 v7, -16, v0
	v_lshl_add_u32 v194, v188, 2, s13
	v_max_i32_e32 v0, 0xffffffed, v0
	v_lshl_add_u32 v3, v3, 2, s13
	v_lshl_add_u32 v5, v5, 2, s13
	v_lshl_add_u32 v6, v6, 2, s13
	v_lshl_add_u32 v7, v7, 2, s13
	v_lshl_add_u32 v0, v0, 2, s13
	ds_read_b32 v188, v2
	ds_read_b32 v189, v3 offset:4
	ds_read_b32 v190, v5 offset:8
	ds_read_b32 v191, v6 offset:12
	ds_read_b32 v192, v7 offset:64
	ds_read_b32 v193, v193 offset:68
	ds_read_b32 v194, v194 offset:72
	ds_read_b32 v195, v0 offset:76
	s_waitcnt lgkmcnt(4)
	v_mfma_f32_16x16x32_bf16 v[188:191], v[172:175], v[92:95], v[188:191]
	s_mov_b64 s[4:5], 0
	s_waitcnt lgkmcnt(0)
	v_mfma_f32_16x16x32_bf16 v[192:195], v[180:183], v[92:95], v[192:195]
	s_nop 0
	v_mfma_f32_16x16x32_bf16 v[188:191], v[176:179], v[96:99], v[188:191]
	v_mfma_f32_16x16x32_bf16 v[192:195], v[184:187], v[96:99], v[192:195]

.LBB0_482:
	s_waitcnt lgkmcnt(11)
	ds_read_b128 v[172:175], v237 offset:55296
	s_waitcnt lgkmcnt(11)
	ds_read_b128 v[176:179], v237 offset:55360
	s_waitcnt lgkmcnt(11)
	ds_read_b128 v[180:183], v237 offset:57600
	s_waitcnt lgkmcnt(11)
	ds_read_b128 v[184:187], v237 offset:57664
	s_waitcnt lgkmcnt(11)
	ds_read_b64_tr_b16 v[160:161], v238 offset:64512
	s_waitcnt lgkmcnt(11)
	ds_read_b64_tr_b16 v[156:157], v238 offset:64544
	s_waitcnt lgkmcnt(11)
	ds_read_b64_tr_b16 v[164:165], v238 offset:64576
	s_waitcnt lgkmcnt(11)
	ds_read_b64_tr_b16 v[168:169], v238 offset:64608
	s_waitcnt lgkmcnt(11)
	ds_read_b64_tr_b16 v[162:163], v239 offset:64512
	s_waitcnt lgkmcnt(11)
	ds_read_b64_tr_b16 v[158:159], v239 offset:64544
	s_waitcnt lgkmcnt(11)
	ds_read_b64_tr_b16 v[166:167], v239 offset:64576
	s_waitcnt lgkmcnt(11)
	ds_read_b64_tr_b16 v[170:171], v239 offset:64608
	s_or_b32 s20, s20, 3
	s_sub_i32 s14, s20, s85
	s_cmp_lt_u32 s14, 9
	s_cselect_b64 s[4:5], -1, 0
	s_cmp_gt_u32 s14, 8
	s_cbranch_scc1 .LBB0_488
	s_cmp_lt_u32 s14, 6
	s_mov_b64 s[70:71], -1
	s_cbranch_scc1 .LBB0_485
	v_lshl_add_u32 v0, s14, 6, v233
	v_max_i32_e32 v188, 0xffffffef, v0
	v_max_i32_e32 v2, 0, v0
	v_lshl_add_u32 v193, v188, 2, s13
	v_max_i32_e32 v188, 0xffffffee, v0
	v_lshl_add_u32 v2, v2, 2, s13
	v_max_i32_e32 v3, -1, v0
	v_max_i32_e32 v5, -2, v0
	v_max_i32_e32 v6, -3, v0
	v_max_i32_e32 v7, -16, v0
	v_lshl_add_u32 v194, v188, 2, s13
	v_max_i32_e32 v0, 0xffffffed, v0
	v_lshl_add_u32 v3, v3, 2, s13
	v_lshl_add_u32 v5, v5, 2, s13
	v_lshl_add_u32 v6, v6, 2, s13
	v_lshl_add_u32 v7, v7, 2, s13
	v_lshl_add_u32 v0, v0, 2, s13
	ds_read_b32 v188, v2
	ds_read_b32 v189, v3 offset:4
	ds_read_b32 v190, v5 offset:8
	ds_read_b32 v191, v6 offset:12
	ds_read_b32 v192, v7 offset:64
	ds_read_b32 v193, v193 offset:68
	ds_read_b32 v194, v194 offset:72
	ds_read_b32 v195, v0 offset:76
	s_waitcnt lgkmcnt(4)
	v_mfma_f32_16x16x32_bf16 v[188:191], v[172:175], v[64:67], v[188:191]
	s_mov_b64 s[70:71], 0
	s_waitcnt lgkmcnt(0)
	v_mfma_f32_16x16x32_bf16 v[192:195], v[180:183], v[64:67], v[192:195]
	s_nop 0
	v_mfma_f32_16x16x32_bf16 v[188:191], v[176:179], v[68:71], v[188:191]
	v_mfma_f32_16x16x32_bf16 v[192:195], v[184:187], v[68:71], v[192:195]

.LBB0_488:
	s_sub_i32 s15, s20, s19
	s_cmp_lt_u32 s15, 9
	s_cselect_b64 s[70:71], -1, 0
	s_cmp_gt_u32 s15, 8
	s_cbranch_scc1 .LBB0_494
	s_cmp_lt_u32 s15, 6
	s_mov_b64 s[72:73], -1
	s_cbranch_scc1 .LBB0_491
	v_lshl_add_u32 v0, s15, 6, v233
	v_max_i32_e32 v188, 0xffffffef, v0
	v_max_i32_e32 v2, 0, v0
	v_lshl_add_u32 v193, v188, 2, s13
	v_max_i32_e32 v188, 0xffffffee, v0
	v_lshl_add_u32 v2, v2, 2, s13
	v_max_i32_e32 v3, -1, v0
	v_max_i32_e32 v5, -2, v0
	v_max_i32_e32 v6, -3, v0
	v_max_i32_e32 v7, -16, v0
	v_lshl_add_u32 v194, v188, 2, s13
	v_max_i32_e32 v0, 0xffffffed, v0
	v_lshl_add_u32 v3, v3, 2, s13
	v_lshl_add_u32 v5, v5, 2, s13
	v_lshl_add_u32 v6, v6, 2, s13
	v_lshl_add_u32 v7, v7, 2, s13
	v_lshl_add_u32 v0, v0, 2, s13
	ds_read_b32 v188, v2
	ds_read_b32 v189, v3 offset:4
	ds_read_b32 v190, v5 offset:8
	ds_read_b32 v191, v6 offset:12
	ds_read_b32 v192, v7 offset:64
	ds_read_b32 v193, v193 offset:68
	ds_read_b32 v194, v194 offset:72
	ds_read_b32 v195, v0 offset:76
	s_waitcnt lgkmcnt(4)
	v_mfma_f32_16x16x32_bf16 v[188:191], v[172:175], v[76:79], v[188:191]
	s_mov_b64 s[72:73], 0
	s_waitcnt lgkmcnt(0)
	v_mfma_f32_16x16x32_bf16 v[192:195], v[180:183], v[76:79], v[192:195]
	s_nop 0
	v_mfma_f32_16x16x32_bf16 v[188:191], v[176:179], v[80:83], v[188:191]
	v_mfma_f32_16x16x32_bf16 v[192:195], v[184:187], v[80:83], v[192:195]

.LBB0_494:
	s_sub_i32 s17, s20, s30
	s_cmp_lt_u32 s17, 9
	s_cselect_b64 s[72:73], -1, 0
	s_cmp_gt_u32 s17, 8
	s_cbranch_scc1 .LBB0_500
	s_cmp_lt_u32 s17, 6
	s_mov_b64 s[74:75], -1
	s_cbranch_scc1 .LBB0_497
	v_lshl_add_u32 v0, s17, 6, v233
	v_max_i32_e32 v188, 0xffffffef, v0
	v_max_i32_e32 v2, 0, v0
	v_lshl_add_u32 v193, v188, 2, s13
	v_max_i32_e32 v188, 0xffffffee, v0
	v_lshl_add_u32 v2, v2, 2, s13
	v_max_i32_e32 v3, -1, v0
	v_max_i32_e32 v5, -2, v0
	v_max_i32_e32 v6, -3, v0
	v_max_i32_e32 v7, -16, v0
	v_lshl_add_u32 v194, v188, 2, s13
	v_max_i32_e32 v0, 0xffffffed, v0
	v_lshl_add_u32 v3, v3, 2, s13
	v_lshl_add_u32 v5, v5, 2, s13
	v_lshl_add_u32 v6, v6, 2, s13
	v_lshl_add_u32 v7, v7, 2, s13
	v_lshl_add_u32 v0, v0, 2, s13
	ds_read_b32 v188, v2
	ds_read_b32 v189, v3 offset:4
	ds_read_b32 v190, v5 offset:8
	ds_read_b32 v191, v6 offset:12
	ds_read_b32 v192, v7 offset:64
	ds_read_b32 v193, v193 offset:68
	ds_read_b32 v194, v194 offset:72
	ds_read_b32 v195, v0 offset:76
	s_waitcnt lgkmcnt(4)
	v_mfma_f32_16x16x32_bf16 v[188:191], v[172:175], v[84:87], v[188:191]
	s_mov_b64 s[74:75], 0
	s_waitcnt lgkmcnt(0)
	v_mfma_f32_16x16x32_bf16 v[192:195], v[180:183], v[84:87], v[192:195]
	s_nop 0
	v_mfma_f32_16x16x32_bf16 v[188:191], v[176:179], v[88:91], v[188:191]
	v_mfma_f32_16x16x32_bf16 v[192:195], v[184:187], v[88:91], v[192:195]

.LBB0_500:
	s_sub_i32 s20, s20, s34
	s_cmp_lt_u32 s20, 9
	s_cselect_b64 s[74:75], -1, 0
	s_cmp_gt_u32 s20, 8
	s_cbranch_scc1 .LBB0_506
	s_cmp_lt_u32 s20, 6
	s_mov_b64 s[76:77], -1
	s_cbranch_scc1 .LBB0_503
	v_lshl_add_u32 v0, s20, 6, v233
	v_max_i32_e32 v188, 0xffffffef, v0
	v_max_i32_e32 v2, 0, v0
	v_lshl_add_u32 v193, v188, 2, s13
	v_max_i32_e32 v188, 0xffffffee, v0
	v_lshl_add_u32 v2, v2, 2, s13
	v_max_i32_e32 v3, -1, v0
	v_max_i32_e32 v5, -2, v0
	v_max_i32_e32 v6, -3, v0
	v_max_i32_e32 v7, -16, v0
	v_lshl_add_u32 v194, v188, 2, s13
	v_max_i32_e32 v0, 0xffffffed, v0
	v_lshl_add_u32 v3, v3, 2, s13
	v_lshl_add_u32 v5, v5, 2, s13
	v_lshl_add_u32 v6, v6, 2, s13
	v_lshl_add_u32 v7, v7, 2, s13
	v_lshl_add_u32 v0, v0, 2, s13
	ds_read_b32 v188, v2
	ds_read_b32 v189, v3 offset:4
	ds_read_b32 v190, v5 offset:8
	ds_read_b32 v191, v6 offset:12
	ds_read_b32 v192, v7 offset:64
	ds_read_b32 v193, v193 offset:68
	ds_read_b32 v194, v194 offset:72
	ds_read_b32 v195, v0 offset:76
	s_waitcnt lgkmcnt(4)
	v_mfma_f32_16x16x32_bf16 v[188:191], v[172:175], v[92:95], v[188:191]
	s_mov_b64 s[76:77], 0
	s_waitcnt lgkmcnt(0)
	v_mfma_f32_16x16x32_bf16 v[192:195], v[180:183], v[92:95], v[192:195]
	s_nop 0
	v_mfma_f32_16x16x32_bf16 v[188:191], v[176:179], v[96:99], v[188:191]
	v_mfma_f32_16x16x32_bf16 v[192:195], v[184:187], v[96:99], v[192:195]

.LBB0_511:
	s_cmp_lt_u32 s14, 6
	s_mov_b64 s[4:5], -1
	s_cbranch_scc1 .LBB0_513
	v_lshl_add_u32 v0, s14, 6, v234
	v_max_i32_e32 v188, 0xffffffef, v0
	v_max_i32_e32 v2, 0, v0
	v_lshl_add_u32 v193, v188, 2, s13
	v_max_i32_e32 v188, 0xffffffee, v0
	v_lshl_add_u32 v2, v2, 2, s13
	v_max_i32_e32 v3, -1, v0
	v_max_i32_e32 v5, -2, v0
	v_max_i32_e32 v6, -3, v0
	v_max_i32_e32 v7, -16, v0
	v_lshl_add_u32 v194, v188, 2, s13
	v_max_i32_e32 v0, 0xffffffed, v0
	v_lshl_add_u32 v3, v3, 2, s13
	v_lshl_add_u32 v5, v5, 2, s13
	v_lshl_add_u32 v6, v6, 2, s13
	v_lshl_add_u32 v7, v7, 2, s13
	v_lshl_add_u32 v0, v0, 2, s13
	ds_read_b32 v188, v2
	ds_read_b32 v189, v3 offset:4
	ds_read_b32 v190, v5 offset:8
	ds_read_b32 v191, v6 offset:12
	ds_read_b32 v192, v7 offset:64
	ds_read_b32 v193, v193 offset:68
	ds_read_b32 v194, v194 offset:72
	ds_read_b32 v195, v0 offset:76
	s_waitcnt lgkmcnt(4)
	v_mfma_f32_16x16x32_bf16 v[188:191], v[172:175], v[64:67], v[188:191]
	s_mov_b64 s[4:5], 0
	s_waitcnt lgkmcnt(0)
	v_mfma_f32_16x16x32_bf16 v[192:195], v[180:183], v[64:67], v[192:195]
	s_nop 0
	v_mfma_f32_16x16x32_bf16 v[188:191], v[176:179], v[68:71], v[188:191]
	v_mfma_f32_16x16x32_bf16 v[192:195], v[184:187], v[68:71], v[192:195]

.LBB0_516:
	s_cmp_lt_u32 s15, 6
	s_mov_b64 s[4:5], -1
	s_cbranch_scc1 .LBB0_518
	v_lshl_add_u32 v0, s15, 6, v234
	v_max_i32_e32 v188, 0xffffffef, v0
	v_max_i32_e32 v2, 0, v0
	v_lshl_add_u32 v193, v188, 2, s13
	v_max_i32_e32 v188, 0xffffffee, v0
	v_lshl_add_u32 v2, v2, 2, s13
	v_max_i32_e32 v3, -1, v0
	v_max_i32_e32 v5, -2, v0
	v_max_i32_e32 v6, -3, v0
	v_max_i32_e32 v7, -16, v0
	v_lshl_add_u32 v194, v188, 2, s13
	v_max_i32_e32 v0, 0xffffffed, v0
	v_lshl_add_u32 v3, v3, 2, s13
	v_lshl_add_u32 v5, v5, 2, s13
	v_lshl_add_u32 v6, v6, 2, s13
	v_lshl_add_u32 v7, v7, 2, s13
	v_lshl_add_u32 v0, v0, 2, s13
	ds_read_b32 v188, v2
	ds_read_b32 v189, v3 offset:4
	ds_read_b32 v190, v5 offset:8
	ds_read_b32 v191, v6 offset:12
	ds_read_b32 v192, v7 offset:64
	ds_read_b32 v193, v193 offset:68
	ds_read_b32 v194, v194 offset:72
	ds_read_b32 v195, v0 offset:76
	s_waitcnt lgkmcnt(4)
	v_mfma_f32_16x16x32_bf16 v[188:191], v[172:175], v[76:79], v[188:191]
	s_mov_b64 s[4:5], 0
	s_waitcnt lgkmcnt(0)
	v_mfma_f32_16x16x32_bf16 v[192:195], v[180:183], v[76:79], v[192:195]
	s_nop 0
	v_mfma_f32_16x16x32_bf16 v[188:191], v[176:179], v[80:83], v[188:191]
	v_mfma_f32_16x16x32_bf16 v[192:195], v[184:187], v[80:83], v[192:195]

.LBB0_521:
	s_cmp_lt_u32 s17, 6
	s_mov_b64 s[4:5], -1
	s_cbranch_scc1 .LBB0_523
	v_lshl_add_u32 v0, s17, 6, v234
	v_max_i32_e32 v188, 0xffffffef, v0
	v_max_i32_e32 v2, 0, v0
	v_lshl_add_u32 v193, v188, 2, s13
	v_max_i32_e32 v188, 0xffffffee, v0
	v_lshl_add_u32 v2, v2, 2, s13
	v_max_i32_e32 v3, -1, v0
	v_max_i32_e32 v5, -2, v0
	v_max_i32_e32 v6, -3, v0
	v_max_i32_e32 v7, -16, v0
	v_lshl_add_u32 v194, v188, 2, s13
	v_max_i32_e32 v0, 0xffffffed, v0
	v_lshl_add_u32 v3, v3, 2, s13
	v_lshl_add_u32 v5, v5, 2, s13
	v_lshl_add_u32 v6, v6, 2, s13
	v_lshl_add_u32 v7, v7, 2, s13
	v_lshl_add_u32 v0, v0, 2, s13
	ds_read_b32 v188, v2
	ds_read_b32 v189, v3 offset:4
	ds_read_b32 v190, v5 offset:8
	ds_read_b32 v191, v6 offset:12
	ds_read_b32 v192, v7 offset:64
	ds_read_b32 v193, v193 offset:68
	ds_read_b32 v194, v194 offset:72
	ds_read_b32 v195, v0 offset:76
	s_waitcnt lgkmcnt(4)
	v_mfma_f32_16x16x32_bf16 v[188:191], v[172:175], v[84:87], v[188:191]
	s_mov_b64 s[4:5], 0
	s_waitcnt lgkmcnt(0)
	v_mfma_f32_16x16x32_bf16 v[192:195], v[180:183], v[84:87], v[192:195]
	s_nop 0
	v_mfma_f32_16x16x32_bf16 v[188:191], v[176:179], v[88:91], v[188:191]
	v_mfma_f32_16x16x32_bf16 v[192:195], v[184:187], v[88:91], v[192:195]

.LBB0_526:
	s_cmp_lt_u32 s20, 6
	s_mov_b64 s[4:5], -1
	s_cbranch_scc1 .LBB0_528
	v_lshl_add_u32 v0, s20, 6, v234
	v_max_i32_e32 v188, 0xffffffef, v0
	v_max_i32_e32 v2, 0, v0
	v_lshl_add_u32 v193, v188, 2, s13
	v_max_i32_e32 v188, 0xffffffee, v0
	v_lshl_add_u32 v2, v2, 2, s13
	v_max_i32_e32 v3, -1, v0
	v_max_i32_e32 v5, -2, v0
	v_max_i32_e32 v6, -3, v0
	v_max_i32_e32 v7, -16, v0
	v_lshl_add_u32 v194, v188, 2, s13
	v_max_i32_e32 v0, 0xffffffed, v0
	v_lshl_add_u32 v3, v3, 2, s13
	v_lshl_add_u32 v5, v5, 2, s13
	v_lshl_add_u32 v6, v6, 2, s13
	v_lshl_add_u32 v7, v7, 2, s13
	v_lshl_add_u32 v0, v0, 2, s13
	ds_read_b32 v188, v2
	ds_read_b32 v189, v3 offset:4
	ds_read_b32 v190, v5 offset:8
	ds_read_b32 v191, v6 offset:12
	ds_read_b32 v192, v7 offset:64
	ds_read_b32 v193, v193 offset:68
	ds_read_b32 v194, v194 offset:72
	ds_read_b32 v195, v0 offset:76
	s_waitcnt lgkmcnt(4)
	v_mfma_f32_16x16x32_bf16 v[188:191], v[172:175], v[92:95], v[188:191]
	s_mov_b64 s[4:5], 0
	s_waitcnt lgkmcnt(0)
	v_mfma_f32_16x16x32_bf16 v[192:195], v[180:183], v[92:95], v[192:195]
	s_nop 0
	v_mfma_f32_16x16x32_bf16 v[188:191], v[176:179], v[96:99], v[188:191]
	v_mfma_f32_16x16x32_bf16 v[192:195], v[184:187], v[96:99], v[192:195]
.LBB0_528:
	s_andn2_b64 vcc, exec, s[4:5]
	s_cbranch_vccnz .LBB0_530
	s_waitcnt lgkmcnt(11)
	v_mfma_f32_16x16x32_bf16 v[172:175], v[172:175], v[92:95], v[152:155]
	s_waitcnt lgkmcnt(9)
	v_mfma_f32_16x16x32_bf16 v[152:155], v[180:183], v[92:95], v[152:155]
	s_nop 0
	v_mfma_f32_16x16x32_bf16 v[188:191], v[176:179], v[96:99], v[172:175]
	s_waitcnt lgkmcnt(8)
	v_mfma_f32_16x16x32_bf16 v[192:195], v[184:187], v[96:99], v[152:155]
